# v7 + removed redundant end-of-tile vmcnt(0)+s_barrier in the 4 GEMM tile loops (next tile prologue overlaps the store drain)
# baseline (speedup 1.0000x reference)
; template <int EPI>
; __device__ __forceinline__ void gemm_tile8p(const bf16_t* __restrict__ Ag, const bf16_t* __restrict__ Bg, int K, int nt, int brow, int bcol,
;                                             char* smem, void* outp, int ldo, int nvalid, int rowoff, int rowlim) {
;     ...
;   __syncthreads();
; template <int K>
; __device__ __forceinline__ void gemm_phase_n1024(CP p, const bf16_t* A, const bf16_t* Bt, char* smem, float* outp) {
;     ...
;   for (int it = 0; it * nb < nitems; ++it) {
;     int id = it * nb + blockIdx.x;
;     if ((it + 1) * nb <= nmain) id = (it * 8 + xcd) * per + slot;
;     if (id >= nitems) break;
.LBB0_86:
	s_or_b64 exec, exec, s[2:3]
	s_cmpk_gt_i32 s12, 0x12b
	s_cselect_b64 s[2:3], -1, 0
.LBB0_87:
	s_and_b64 vcc, exec, s[2:3]
	s_cbranch_vccnz .LBB0_165

; template <int EPI>
; __device__ __forceinline__ void gemm_tile8p(const bf16_t* __restrict__ Ag, const bf16_t* __restrict__ Bg, int K, int nt, int brow, int bcol,
;                                             char* smem, void* outp, int ldo, int nvalid, int rowoff, int rowlim) {
;     ...
;   __syncthreads();
.LBB0_168:
	s_or_b64 exec, exec, s[2:3]
	s_waitcnt lgkmcnt(0)

; template <int EPI>
; __device__ __forceinline__ void gemm_tile8p(const bf16_t* __restrict__ Ag, const bf16_t* __restrict__ Bg, int K, int nt, int brow, int bcol,
;                                             char* smem, void* outp, int ldo, int nvalid, int rowoff, int rowlim) {
;     ...
;   __syncthreads();
; template <int K>
; __device__ __forceinline__ void gemm_phase_n1024(CP p, const bf16_t* A, const bf16_t* Bt, char* smem, float* outp) {
;     ...
;   for (int it = 0; it * nb < nitems; ++it) {
;     int id = it * nb + blockIdx.x;
;     if ((it + 1) * nb <= nmain) id = (it * 8 + xcd) * per + slot;
;     if (id >= nitems) break;
.LBB0_304:
	s_or_b64 exec, exec, s[2:3]
	s_cmpk_gt_i32 s15, 0x10f
	s_cselect_b64 s[2:3], -1, 0
.LBB0_305:
	s_and_b64 vcc, exec, s[2:3]
	s_cbranch_vccnz .LBB0_382

; template <int EPI>
; __device__ __forceinline__ void gemm_tile8p(const bf16_t* __restrict__ Ag, const bf16_t* __restrict__ Bg, int K, int nt, int brow, int bcol,
;                                             char* smem, void* outp, int ldo, int nvalid, int rowoff, int rowlim) {
;     ...
;   __syncthreads();
; template <int EPI>
; __device__ __forceinline__ void gemm_phase256(const bf16_t* A, const bf16_t* Bt, int K, int NT, char* smem, void* outp, int ldo, int nvalid) {
;     ...
;   for (int it = 0; it * nb < ntiles; ++it) {
;     const int k = (it * 8 + xcd) * per + slot;
;     if (k >= ntiles) continue;
;     const int panel = k / (TM * 8);
;     const int w = min(8, NT - panel * 8);
;     const int idx = k - panel * TM * 8;
;     const int tm = idx / w, tn = panel * 8 + idx % w;
;     gemm_tile8p<EPI>(A, Bt, K, K >> 6, tm * 256, tn * 256, smem, outp, ldo, nvalid, tm * 256, R - tm * 256);
.LBB0_1060:
	s_or_b64 exec, exec, s[2:3]
.LBB0_1061:
	s_add_i32 s10, s10, 1
	s_mul_i32 s2, s10, s46
	s_cmpk_gt_i32 s2, 0x38d
	s_cbranch_scc1 .LBB0_1325
